# mask-from-mask VALU pairs (v_cndmask 0/1 + v_cmp_ne) replaced by one s_andn2_b64 at 6 sites (NA / MLA step loops, FFN-up / FFN-down next-tile flag)
# speedup vs baseline: 1.0022x; 1.0022x over previous
.LBB0_388:
	s_andn2_b64 s[6:7], exec, s[14:15]
	s_andn2_b64 vcc, exec, s[14:15]
	s_cbranch_vccnz .LBB0_390
	v_add_co_u32_e32 v2, vcc, 0xfff41000, v158
	s_nop 1
	v_addc_co_u32_e32 v3, vcc, -1, v159, vcc
	global_load_dwordx4 v[136:139], v[2:3], off offset:-2048
.LBB0_390:
	s_add_i32 s23, s31, -4
	s_cmp_ge_i32 s23, s9
	s_cselect_b64 s[20:21], -1, 0
	s_cmp_lt_i32 s23, s11
	s_cselect_b64 s[38:39], -1, 0
	s_and_b64 s[20:21], s[20:21], s[38:39]
	s_andn2_b64 s[72:73], exec, s[20:21]
	s_andn2_b64 vcc, exec, s[20:21]
	s_cbranch_vccnz .LBB0_430
	v_add3_u32 v0, v163, s31, -4
	v_cmp_gt_u32_e32 vcc, 8, v0
	s_and_b64 s[38:39], vcc, s[40:41]
	v_mov_b32_e32 v117, 0xff800000
	v_mov_b32_e32 v116, 0xff800000
	s_and_saveexec_b64 s[20:21], s[38:39]
	s_cbranch_execz .LBB0_393
	v_add_u32_e32 v0, s30, v164
	ds_read_b32 v0, v0 offset:43904
	s_waitcnt lgkmcnt(0)
	v_add_f32_e32 v116, v52, v0

.LBB0_444:
	s_and_b64 s[16:17], s[20:21], s[22:23]
	s_andn2_b64 s[6:7], exec, s[16:17]
	s_andn2_b64 vcc, exec, s[16:17]
	s_cbranch_vccnz .LBB0_485
	v_add3_u32 v0, v163, s31, -3
	v_cmp_gt_u32_e32 vcc, 8, v0
	s_and_b64 s[18:19], vcc, s[40:41]
	v_mov_b32_e32 v117, 0xff800000
	v_add_u32_e32 v0, s30, v164
	v_mov_b32_e32 v116, 0xff800000
	s_and_saveexec_b64 s[16:17], s[18:19]
	s_cbranch_execz .LBB0_447
	ds_read_b32 v2, v0 offset:44028
	s_waitcnt lgkmcnt(0)
	v_add_f32_e32 v116, v84, v2

; template <class Epi, bool SEG>
; __device__ __forceinline__ void gemm_phase(LAS unsigned char* lds, const Gemm g, const int G, const int cidx, const Epi& E) {
;     ...
;         const bool has_next = S.next(ui + 1, nxt);
;         const char* nA = has_next ? (const char*)g.A + (long)nxt.pm * (long)tstepA + aoff0 : cA; const char* nB = has_next ? (const char*)g.Bt + (size_t)nxt.pn * tstepB : cB;
.LBB0_783:
	s_andn2_b64 s[50:51], exec, s[6:7]
	s_andn2_b64 vcc, exec, s[6:7]
	s_mov_b64 s[16:17], s[40:41]
	s_cbranch_vccnz .LBB0_785
	s_mul_i32 s16, s30, 0x7c000
	s_mul_hi_i32 s15, s30, 0x7c000
	s_add_u32 s16, s82, s16
	s_addc_u32 s15, s83, s15
	s_add_u32 s16, s16, 0xfffff800
	s_addc_u32 s17, s15, -1

; template <class Epi, bool SEG>
; __device__ __forceinline__ void gemm_phase(LAS unsigned char* lds, const Gemm g, const int G, const int cidx, const Epi& E) {
;     ...
;         const bool has_next = S.next(ui + 1, nxt);
;         const char* nA = has_next ? (const char*)g.A + (long)nxt.pm * (long)tstepA + aoff0 : cA; const char* nB = has_next ? (const char*)g.Bt + (size_t)nxt.pn * tstepB : cB;
.LBB0_953:
	s_nop 0
	s_andn2_b64 s[44:45], exec, s[6:7]
	s_andn2_b64 vcc, exec, s[6:7]
	s_mov_b64 s[6:7], s[18:19]
	s_cbranch_vccnz .LBB0_955
	s_mul_i32 s6, s51, 0x160000
	s_mul_hi_i32 s7, s51, 0x160000
	s_add_u32 s6, s4, s6
	s_addc_u32 s7, s5, s7

.LBB0_1154:
	s_andn2_b64 s[6:7], exec, s[14:15]
	s_andn2_b64 vcc, exec, s[14:15]
	s_cbranch_vccnz .LBB0_1156
	v_add_co_u32_e32 v98, vcc, 0x20500000, v214
	s_nop 1
	v_addc_co_u32_e32 v99, vcc, 0, v215, vcc
	global_load_dwordx4 v[150:153], v[98:99], off offset:128
